# FFN1 main loop with direct HBM->LDS loads (global_load_lds_dwordx4), XOR-swizzled lane-linear LDS image, no VGPR staging / ds_write pass
# speedup vs baseline: 1.0076x; 1.0030x over previous
; DI int TIDX() { int t = threadIdx.x; asm volatile("" : "+v"(t)); return t; }
; #define XCD_LOOP_W(Mt, ntn) const int xcd_ = BIDX() & 7; const int Mx_ = ((Mt) + 7) >> 3; for (int u_ = BIDX() >> 3; u_ < Mx_ * (ntn); u_ += (int)(gridDim.x >> 3))
; template <class BR>
; DI void gemm_tile_w(const h16* __restrict__ A, int lda, const h16* __restrict__ B, int ldb, BR brow, int K, f32x16 (&acc)[4][2], h16* sm) {
;   const int tid = TIDX(), lane = tid & 63, w = tid >> 6, wm = w >> 1, wn = w & 1, r = lane & 31, hh = lane >> 5;
;   const unsigned ao = (unsigned)(tid >> 2) * (unsigned)lda + (unsigned)(tid & 3) * 8u;
;   const unsigned bo0 = (unsigned)brow(tid >> 2) * (unsigned)ldb + (unsigned)(tid & 3) * 8u;
;   const unsigned bo1 = (unsigned)brow((tid >> 2) + 64) * (unsigned)ldb + (unsigned)(tid & 3) * 8u;
;   const h16* ag = A;
;   const h16* bg = B;
;   u32x4 ra0[4], rb0[2], ra1[4], rb1[2];
; #pragma unroll
;   for (int i = 0; i < 4; ++i) ra0[i] = *(const u32x4*)(ag + (ao + (unsigned)i * 64u * (unsigned)lda));
;   rb0[0] = *(const u32x4*)(bg + bo0);
;   rb0[1] = *(const u32x4*)(bg + bo1);
;   ag += 32; bg += 32;
; #pragma unroll
;   for (int i = 0; i < 4; ++i) ra1[i] = *(const u32x4*)(ag + (ao + (unsigned)i * 64u * (unsigned)lda));
;   rb1[0] = *(const u32x4*)(bg + bo0);
;   rb1[1] = *(const u32x4*)(bg + bo1);
;   const int nk = K >> 5;
;   const int wofs = (tid >> 2) * LS2 + (tid & 3) * 8;
; DI void phase_ffn1(const P& p, int l, int hf, char* smem) {
;     ...
;   XCD_LOOP_W(Mt, 44) {
;     int mt_, nt_;
;     tile_map(u_, Mx_, 44, xcd_, mt_, nt_);
;     if (mt_ >= Mt) continue;
;     const int m0 = mt0 * 128 + mt_ * 256, c0 = nt_ * 64;
;     f32x16 acc[4][2];
;     zero_acc_w(acc);
;     gemm_tile_w(h2 + (size_t)m0 * 1024, 1024, W, 1024,
;                 [&](int rr) { const int q = rr & 63; return ((q >> 5) ? 2816 : 0) + c0 + (rr >> 6) * 32 + (q & 31); }, 1024, acc, (h16*)smem);
.LBB0_71:
	s_mul_hi_i32 s12, s22, 0x2e8ba2e9
	s_lshr_b32 s13, s12, 31
	s_ashr_i32 s12, s12, 6
	s_add_i32 s12, s12, s13
	s_lshl_b32 s14, s12, 3
	s_sub_i32 s13, s21, s14
	s_min_i32 s15, s13, 8
	s_abs_i32 s13, s15
	v_cvt_f32_u32_e32 v0, s13
	s_sub_i32 s18, 0, s13
	s_mulk_i32 s12, 0xfea0
	s_add_i32 s12, s12, s22
	v_rcp_iflag_f32_e32 v0, v0
	s_abs_i32 s16, s12
	s_xor_b32 s17, s12, s15
	s_ashr_i32 s17, s17, 31
	v_mul_f32_e32 v0, 0x4f7ffffe, v0
	v_cvt_u32_f32_e32 v0, v0
	s_nop 0
	v_readfirstlane_b32 s19, v0
	s_mul_i32 s18, s18, s19
	s_mul_hi_u32 s18, s19, s18
	s_add_i32 s19, s19, s18
	s_mul_hi_u32 s18, s16, s19
	s_mul_i32 s19, s18, s13
	s_sub_i32 s16, s16, s19
	s_add_i32 s26, s18, 1
	s_sub_i32 s19, s16, s13
	s_cmp_ge_u32 s16, s13
	s_cselect_b32 s18, s26, s18
	s_cselect_b32 s16, s19, s16
	s_add_i32 s19, s18, 1
	s_cmp_ge_u32 s16, s13
	s_cselect_b32 s13, s19, s18
	s_xor_b32 s13, s13, s17
	s_sub_i32 s13, s13, s17
	s_add_i32 s14, s14, s38
	s_mul_i32 s15, s15, s13
	s_add_i32 s14, s14, s12
	s_sub_i32 s12, s14, s15
	s_cmp_ge_i32 s12, s20
	s_cbranch_scc1 .LBB0_70
	v_mov_b32_e32 v18, v203
	s_lshl_b32 s26, s13, 6
	s_lshl_b32 s12, s12, 8
	v_ashrrev_i32_e32 v19, 2, v18
	v_bfe_i32 v2, v18, 7, 1
	v_and_b32_e32 v2, 0xb00, v2
	v_lshrrev_b32_e32 v3, 3, v18
	v_and_or_b32 v4, v19, 31, s26
	v_and_b32_e32 v3, 0x3fffe0, v3
	v_add_u32_e32 v2, v2, v4
	v_add_u32_e32 v10, v2, v3
	v_add_u32_e32 v3, 64, v19
	s_ashr_i32 s13, s12, 31
	v_lshlrev_b32_e32 v0, 3, v18
	v_lshrrev_b32_e32 v3, 1, v3
	s_lshl_b64 s[14:15], s[12:13], 11
	v_and_b32_e32 v20, 24, v0
	v_bfe_u32 v21, v18, 4, 2
	v_lshlrev_b32_e32 v21, 3, v21
	v_xor_b32_e32 v20, v20, v21
	v_and_b32_e32 v3, 0x3fffe0, v3
	s_add_u32 s14, s24, s14
	v_add_u32_e32 v11, v2, v3
	v_lshl_or_b32 v210, v10, 10, v20
	v_mov_b32_e32 v211, v1
	s_addc_u32 s15, s25, s15
	v_lshl_or_b32 v0, v19, 10, v20
	v_lshl_or_b32 v212, v11, 10, v20
	v_lshlrev_b64 v[10:11], 1, v[210:211]
	v_mov_b32_e32 v213, v1
	v_lshl_add_u64 v[2:3], v[0:1], 1, s[14:15]
	v_add_u32_e32 v204, 0x10000, v0
	v_mov_b32_e32 v205, v1
	v_add_u32_e32 v206, 0x20000, v0
	v_mov_b32_e32 v207, v1
	v_add_u32_e32 v208, 0x30000, v0
	v_mov_b32_e32 v209, v1
	v_lshl_add_u64 v[12:13], s[6:7], 0, v[10:11]
	v_lshlrev_b64 v[14:15], 1, v[212:213]
	v_lshl_add_u64 v[4:5], v[204:205], 1, s[14:15]
	v_lshl_add_u64 v[6:7], v[206:207], 1, s[14:15]
	v_lshl_add_u64 v[8:9], v[208:209], 1, s[14:15]
	v_lshl_add_u64 v[16:17], s[6:7], 0, v[14:15]
	v_readfirstlane_b32 s18, v203
	s_nop 3
	s_lshr_b32 s18, s18, 6
	s_lshl_b32 s18, s18, 10
	v_and_b32_e32 v136, 31, v203
	v_bfe_u32 v137, v203, 5, 1
	v_bfe_u32 v138, v203, 2, 2
	v_xor_b32_e32 v137, v137, v138
	v_lshlrev_b32_e32 v137, 4, v137
	v_lshl_or_b32 v136, v136, 6, v137
	v_lshrrev_b32_e32 v138, 7, v203
	v_lshl_add_u32 v130, v138, 13, v136
	v_bfe_u32 v138, v203, 6, 1
	v_lshl_add_u32 v132, v138, 12, v136
	v_xor_b32_e32 v131, 32, v130
	v_xor_b32_e32 v133, 32, v132
	s_mov_b64 s[16:17], s[6:7]
	s_add_u32 m0, s18, 0x0
	v_lshl_add_u64 v[134:135], v[0:1], 1, s[14:15]
	global_load_lds_dwordx4 v[134:135], off
	s_add_u32 m0, s18, 0x1000
	v_lshl_add_u64 v[134:135], v[204:205], 1, s[14:15]
	global_load_lds_dwordx4 v[134:135], off
	s_add_u32 m0, s18, 0x2000
	v_lshl_add_u64 v[134:135], v[206:207], 1, s[14:15]
	global_load_lds_dwordx4 v[134:135], off
	s_add_u32 m0, s18, 0x3000
	v_lshl_add_u64 v[134:135], v[208:209], 1, s[14:15]
	global_load_lds_dwordx4 v[134:135], off
	s_add_u32 m0, s18, 0x4000
	v_lshl_add_u64 v[134:135], v[210:211], 1, s[16:17]
	global_load_lds_dwordx4 v[134:135], off
	s_add_u32 m0, s18, 0x5000
	v_lshl_add_u64 v[134:135], v[212:213], 1, s[16:17]
	global_load_lds_dwordx4 v[134:135], off
	s_add_u32 s14, s14, 64
	s_addc_u32 s15, s15, 0
	s_add_u32 s16, s16, 64
	s_addc_u32 s17, s17, 0
	v_mov_b32_e32 v2, 0
	s_mov_b32 s13, 0
	v_mov_b32_e32 v3, v2
	v_mov_b32_e32 v4, v2
	v_mov_b32_e32 v5, v2
	v_mov_b32_e32 v6, v2
	v_mov_b32_e32 v7, v2
	v_mov_b32_e32 v8, v2
	v_mov_b32_e32 v9, v2
	v_mov_b32_e32 v10, v2
	v_mov_b32_e32 v11, v2
	v_mov_b32_e32 v12, v2
	v_mov_b32_e32 v13, v2
	v_mov_b32_e32 v14, v2
	v_mov_b32_e32 v15, v2
	v_mov_b32_e32 v16, v2
	v_mov_b32_e32 v17, v2
	v_mov_b32_e32 v18, v2
	v_mov_b32_e32 v19, v2
	v_mov_b32_e32 v20, v2
	v_mov_b32_e32 v21, v2
	v_mov_b32_e32 v22, v2
	v_mov_b32_e32 v23, v2
	v_mov_b32_e32 v24, v2
	v_mov_b32_e32 v25, v2
	v_mov_b32_e32 v26, v2
	v_mov_b32_e32 v27, v2
	v_mov_b32_e32 v28, v2
	v_mov_b32_e32 v29, v2
	v_mov_b32_e32 v30, v2
	v_mov_b32_e32 v31, v2
	v_mov_b32_e32 v32, v2
	v_mov_b32_e32 v33, v2
	v_mov_b32_e32 v34, v2
	v_mov_b32_e32 v35, v2
	v_mov_b32_e32 v36, v2
	v_mov_b32_e32 v37, v2
	v_mov_b32_e32 v38, v2
	v_mov_b32_e32 v39, v2
	v_mov_b32_e32 v40, v2
	v_mov_b32_e32 v41, v2
	v_mov_b32_e32 v42, v2
	v_mov_b32_e32 v43, v2
	v_mov_b32_e32 v44, v2
	v_mov_b32_e32 v45, v2
	v_mov_b32_e32 v46, v2
	v_mov_b32_e32 v47, v2
	v_mov_b32_e32 v48, v2
	v_mov_b32_e32 v49, v2
	s_waitcnt vmcnt(15)
	v_mov_b32_e32 v50, v2
	v_mov_b32_e32 v51, v2
	v_mov_b32_e32 v52, v2
	v_mov_b32_e32 v53, v2
	s_waitcnt vmcnt(14)
	v_mov_b32_e32 v54, v2
	v_mov_b32_e32 v55, v2
	v_mov_b32_e32 v56, v2
	v_mov_b32_e32 v57, v2
	s_waitcnt vmcnt(13)
	v_mov_b32_e32 v58, v2
	v_mov_b32_e32 v59, v2
	v_mov_b32_e32 v60, v2
	v_mov_b32_e32 v61, v2
	s_waitcnt vmcnt(12)
	v_mov_b32_e32 v62, v2
	v_mov_b32_e32 v63, v2
	v_mov_b32_e32 v64, v2
	v_mov_b32_e32 v65, v2
	v_mov_b32_e32 v66, v2
	v_mov_b32_e32 v67, v2
	v_mov_b32_e32 v68, v2
	v_mov_b32_e32 v69, v2
	v_mov_b32_e32 v70, v2
	v_mov_b32_e32 v71, v2
	v_mov_b32_e32 v72, v2
	v_mov_b32_e32 v73, v2
	v_mov_b32_e32 v74, v2
	v_mov_b32_e32 v75, v2
	v_mov_b32_e32 v76, v2
	v_mov_b32_e32 v77, v2
	v_mov_b32_e32 v78, v2
	v_mov_b32_e32 v79, v2
	v_mov_b32_e32 v80, v2
	v_mov_b32_e32 v81, v2
	v_mov_b32_e32 v82, v2
	v_mov_b32_e32 v83, v2
	v_mov_b32_e32 v84, v2
	v_mov_b32_e32 v85, v2
	v_mov_b32_e32 v86, v2
	v_mov_b32_e32 v87, v2
	v_mov_b32_e32 v88, v2
	v_mov_b32_e32 v89, v2
	v_mov_b32_e32 v90, v2
	v_mov_b32_e32 v91, v2
	v_mov_b32_e32 v92, v2
	v_mov_b32_e32 v93, v2
	v_mov_b32_e32 v94, v2
	v_mov_b32_e32 v95, v2
	v_mov_b32_e32 v96, v2
	v_mov_b32_e32 v97, v2
	v_mov_b32_e32 v98, v2
	v_mov_b32_e32 v99, v2
	v_mov_b32_e32 v100, v2
	v_mov_b32_e32 v101, v2
	v_mov_b32_e32 v102, v2
	v_mov_b32_e32 v103, v2
	v_mov_b32_e32 v104, v2
	v_mov_b32_e32 v105, v2
	v_mov_b32_e32 v106, v2
	v_mov_b32_e32 v107, v2
	v_mov_b32_e32 v108, v2
	v_mov_b32_e32 v109, v2
	v_mov_b32_e32 v110, v2
	v_mov_b32_e32 v111, v2
	v_mov_b32_e32 v112, v2
	v_mov_b32_e32 v113, v2
	v_mov_b32_e32 v114, v2
	v_mov_b32_e32 v115, v2
	v_mov_b32_e32 v116, v2
	v_mov_b32_e32 v117, v2
	v_mov_b32_e32 v118, v2
	v_mov_b32_e32 v119, v2
	v_mov_b32_e32 v120, v2
	v_mov_b32_e32 v121, v2
	v_mov_b32_e32 v122, v2
	v_mov_b32_e32 v123, v2
	v_mov_b32_e32 v124, v2
	v_mov_b32_e32 v125, v2
	v_mov_b32_e32 v126, v2
	v_mov_b32_e32 v127, v2
	v_mov_b32_e32 v128, v2
	v_mov_b32_e32 v129, v2
	s_waitcnt vmcnt(0)
	s_barrier
; template <class BR>
; DI void gemm_tile_w(const h16* __restrict__ A, int lda, const h16* __restrict__ B, int ldb, BR brow, int K, f32x16 (&acc)[4][2], h16* sm) {
;     ...
;   for (int kt = 0; kt < nk; kt += 2) {
;     WIDE_HALF(ra0, rb0, 0, kt)
;     WIDE_HALF(ra1, rb1, 1, kt + 1)
;   }
.Lfg_stage0:
	ds_read_b128 v[178:181], v130 offset:0
	ds_read_b128 v[182:185], v130 offset:2048
	ds_read_b128 v[186:189], v130 offset:4096
	ds_read_b128 v[190:193], v130 offset:6144
	ds_read_b128 v[194:197], v132 offset:16384
	ds_read_b128 v[198:201], v132 offset:18432
	ds_read_b128 v[216:219], v131 offset:0
	ds_read_b128 v[220:223], v131 offset:2048
	ds_read_b128 v[226:229], v131 offset:4096
	ds_read_b128 v[230:233], v131 offset:6144
	ds_read_b128 v[234:237], v133 offset:16384
	ds_read_b128 v[240:243], v133 offset:18432
	s_cmp_ge_u32 s13, 31
	s_cbranch_scc1 .Lfg_nl0
	s_add_u32 m0, s18, 0x6000
	v_lshl_add_u64 v[134:135], v[0:1], 1, s[14:15]
	global_load_lds_dwordx4 v[134:135], off
	s_add_u32 m0, s18, 0x7000
	v_lshl_add_u64 v[134:135], v[204:205], 1, s[14:15]
	global_load_lds_dwordx4 v[134:135], off
	s_add_u32 m0, s18, 0x8000
	v_lshl_add_u64 v[134:135], v[206:207], 1, s[14:15]
	global_load_lds_dwordx4 v[134:135], off
	s_add_u32 m0, s18, 0x9000
	v_lshl_add_u64 v[134:135], v[208:209], 1, s[14:15]
	global_load_lds_dwordx4 v[134:135], off
	s_add_u32 m0, s18, 0xa000
	v_lshl_add_u64 v[134:135], v[210:211], 1, s[16:17]
	global_load_lds_dwordx4 v[134:135], off
	s_add_u32 m0, s18, 0xb000
	v_lshl_add_u64 v[134:135], v[212:213], 1, s[16:17]
	global_load_lds_dwordx4 v[134:135], off
	s_add_u32 s14, s14, 64
	s_addc_u32 s15, s15, 0
	s_add_u32 s16, s16, 64
	s_addc_u32 s17, s17, 0
.Lfg_nl0:
	s_waitcnt lgkmcnt(6)
	v_mfma_f32_32x32x16_f16 v[114:129], v[178:181], v[194:197], v[114:129]
	v_mfma_f32_32x32x16_f16 v[98:113], v[178:181], v[198:201], v[98:113]
	v_mfma_f32_32x32x16_f16 v[82:97], v[182:185], v[194:197], v[82:97]
	v_mfma_f32_32x32x16_f16 v[66:81], v[182:185], v[198:201], v[66:81]
	v_mfma_f32_32x32x16_f16 v[50:65], v[186:189], v[194:197], v[50:65]
	v_mfma_f32_32x32x16_f16 v[34:49], v[186:189], v[198:201], v[34:49]
	v_mfma_f32_32x32x16_f16 v[18:33], v[190:193], v[194:197], v[18:33]
	v_mfma_f32_32x32x16_f16 v[2:17], v[190:193], v[198:201], v[2:17]
	s_waitcnt lgkmcnt(0)
	v_mfma_f32_32x32x16_f16 v[114:129], v[216:219], v[234:237], v[114:129]
	v_mfma_f32_32x32x16_f16 v[98:113], v[216:219], v[240:243], v[98:113]
	v_mfma_f32_32x32x16_f16 v[82:97], v[220:223], v[234:237], v[82:97]
	v_mfma_f32_32x32x16_f16 v[66:81], v[220:223], v[240:243], v[66:81]
	v_mfma_f32_32x32x16_f16 v[50:65], v[226:229], v[234:237], v[50:65]
	v_mfma_f32_32x32x16_f16 v[34:49], v[226:229], v[240:243], v[34:49]
	v_mfma_f32_32x32x16_f16 v[18:33], v[230:233], v[234:237], v[18:33]
	v_mfma_f32_32x32x16_f16 v[2:17], v[230:233], v[240:243], v[2:17]
	s_add_i32 s13, s13, 1
	s_waitcnt vmcnt(0)
	s_barrier
.Lfg_stage1:
	ds_read_b128 v[178:181], v130 offset:24576
	ds_read_b128 v[182:185], v130 offset:26624
	ds_read_b128 v[186:189], v130 offset:28672
	ds_read_b128 v[190:193], v130 offset:30720
	ds_read_b128 v[194:197], v132 offset:40960
	ds_read_b128 v[198:201], v132 offset:43008
	ds_read_b128 v[216:219], v131 offset:24576
	ds_read_b128 v[220:223], v131 offset:26624
	ds_read_b128 v[226:229], v131 offset:28672
	ds_read_b128 v[230:233], v131 offset:30720
	ds_read_b128 v[234:237], v133 offset:40960
	ds_read_b128 v[240:243], v133 offset:43008
	s_cmp_ge_u32 s13, 31
	s_cbranch_scc1 .Lfg_nl1
	s_add_u32 m0, s18, 0x0
	v_lshl_add_u64 v[134:135], v[0:1], 1, s[14:15]
	global_load_lds_dwordx4 v[134:135], off
	s_add_u32 m0, s18, 0x1000
	v_lshl_add_u64 v[134:135], v[204:205], 1, s[14:15]
	global_load_lds_dwordx4 v[134:135], off
	s_add_u32 m0, s18, 0x2000
	v_lshl_add_u64 v[134:135], v[206:207], 1, s[14:15]
	global_load_lds_dwordx4 v[134:135], off
	s_add_u32 m0, s18, 0x3000
	v_lshl_add_u64 v[134:135], v[208:209], 1, s[14:15]
	global_load_lds_dwordx4 v[134:135], off
	s_add_u32 m0, s18, 0x4000
	v_lshl_add_u64 v[134:135], v[210:211], 1, s[16:17]
	global_load_lds_dwordx4 v[134:135], off
	s_add_u32 m0, s18, 0x5000
	v_lshl_add_u64 v[134:135], v[212:213], 1, s[16:17]
	global_load_lds_dwordx4 v[134:135], off
	s_add_u32 s14, s14, 64
	s_addc_u32 s15, s15, 0
	s_add_u32 s16, s16, 64
	s_addc_u32 s17, s17, 0
.Lfg_nl1:
	s_waitcnt lgkmcnt(6)
	v_mfma_f32_32x32x16_f16 v[114:129], v[178:181], v[194:197], v[114:129]
	v_mfma_f32_32x32x16_f16 v[98:113], v[178:181], v[198:201], v[98:113]
	v_mfma_f32_32x32x16_f16 v[82:97], v[182:185], v[194:197], v[82:97]
	v_mfma_f32_32x32x16_f16 v[66:81], v[182:185], v[198:201], v[66:81]
	v_mfma_f32_32x32x16_f16 v[50:65], v[186:189], v[194:197], v[50:65]
	v_mfma_f32_32x32x16_f16 v[34:49], v[186:189], v[198:201], v[34:49]
	v_mfma_f32_32x32x16_f16 v[18:33], v[190:193], v[194:197], v[18:33]
	v_mfma_f32_32x32x16_f16 v[2:17], v[190:193], v[198:201], v[2:17]
	s_waitcnt lgkmcnt(0)
	v_mfma_f32_32x32x16_f16 v[114:129], v[216:219], v[234:237], v[114:129]
	v_mfma_f32_32x32x16_f16 v[98:113], v[216:219], v[240:243], v[98:113]
	v_mfma_f32_32x32x16_f16 v[82:97], v[220:223], v[234:237], v[82:97]
	v_mfma_f32_32x32x16_f16 v[66:81], v[220:223], v[240:243], v[66:81]
	v_mfma_f32_32x32x16_f16 v[50:65], v[226:229], v[234:237], v[50:65]
	v_mfma_f32_32x32x16_f16 v[34:49], v[226:229], v[240:243], v[34:49]
	v_mfma_f32_32x32x16_f16 v[18:33], v[230:233], v[234:237], v[18:33]
	v_mfma_f32_32x32x16_f16 v[2:17], v[230:233], v[240:243], v[2:17]
	s_add_i32 s13, s13, 1
	s_cmp_ge_u32 s13, 32
	s_cbranch_scc1 .LBB0_69
	s_waitcnt vmcnt(0)
	s_barrier
	s_branch .Lfg_stage0
